# relaxed barrier polling: s_sleep 1 -> s_sleep 3 in the eleven fast-path group-barrier poll loops (less traffic on the arrive counter line)
# speedup vs baseline: 1.0085x; 1.0085x over previous
; __device__ __forceinline__ unsigned xb_ld(unsigned* p)              { return __hip_atomic_load(p, __ATOMIC_RELAXED, __HIP_MEMORY_SCOPE_AGENT); }
; #define XB_SPIN(cond, bar) do { unsigned _sp = 0; while (cond) { __builtin_amdgcn_s_sleep(1); \
;     if ((++_sp & 255u) == 0u) { if (xb_ld(&(bar)[XB_TMO])) break; if (_sp > XB_SPIN_CAP) { atomicAdd(&(bar)[XB_TMO], 1u); break; } } } } while (0)
; __device__ __forceinline__ void grp_barrier(const XcdBarrier& b, unsigned gsz) {
;     ...
;             XB_SPIN(xb_ld(&bar[XB_XGEN(b.x)]) == gen, bar);
.Lgb_poll0:
	s_waitcnt vmcnt(0)
	v_sub_u32_e32 v3, v7, v6
	v_cmp_gt_i32_e32 vcc, 0, v3
	s_cbranch_vccz .Lgb_done0
	s_sleep 3
	s_add_u32 s3, s3, 1
	s_cmp_lt_u32 s3, 0x40000
	s_cbranch_scc0 .Lgb_done0
	global_load_dword v7, v202, s[8:9] offset:1024 sc1
	s_branch .Lgb_poll0

; __device__ __forceinline__ unsigned xb_ld(unsigned* p)              { return __hip_atomic_load(p, __ATOMIC_RELAXED, __HIP_MEMORY_SCOPE_AGENT); }
; #define XB_SPIN(cond, bar) do { unsigned _sp = 0; while (cond) { __builtin_amdgcn_s_sleep(1); \
;     if ((++_sp & 255u) == 0u) { if (xb_ld(&(bar)[XB_TMO])) break; if (_sp > XB_SPIN_CAP) { atomicAdd(&(bar)[XB_TMO], 1u); break; } } } } while (0)
; __device__ __forceinline__ void grp_barrier(const XcdBarrier& b, unsigned gsz) {
;     ...
;             XB_SPIN(xb_ld(&bar[XB_XGEN(b.x)]) == gen, bar);
.Lgb_poll7:
	s_waitcnt vmcnt(0)
	v_sub_u32_e32 v3, v7, v6
	v_cmp_gt_i32_e32 vcc, 0, v3
	s_cbranch_vccz .Lgb_done7
	s_sleep 3
	s_add_u32 s3, s3, 1
	s_cmp_lt_u32 s3, 0x40000
	s_cbranch_scc0 .Lgb_done7
	global_load_dword v7, v202, s[12:13] offset:1024 sc1
	s_branch .Lgb_poll7

; __device__ __forceinline__ unsigned xb_ld(unsigned* p)              { return __hip_atomic_load(p, __ATOMIC_RELAXED, __HIP_MEMORY_SCOPE_AGENT); }
; #define XB_SPIN(cond, bar) do { unsigned _sp = 0; while (cond) { __builtin_amdgcn_s_sleep(1); \
;     if ((++_sp & 255u) == 0u) { if (xb_ld(&(bar)[XB_TMO])) break; if (_sp > XB_SPIN_CAP) { atomicAdd(&(bar)[XB_TMO], 1u); break; } } } } while (0)
; __device__ __forceinline__ void grp_barrier(const XcdBarrier& b, unsigned gsz) {
;     ...
;             XB_SPIN(xb_ld(&bar[XB_XGEN(b.x)]) == gen, bar);
.Lgb_poll9:
	s_waitcnt vmcnt(0)
	v_sub_u32_e32 v3, v7, v6
	v_cmp_gt_i32_e32 vcc, 0, v3
	s_cbranch_vccz .Lgb_done9
	s_sleep 3
	s_add_u32 s3, s3, 1
	s_cmp_lt_u32 s3, 0x40000
	s_cbranch_scc0 .Lgb_done9
	global_load_dword v7, v202, s[10:11] offset:1024 sc1
	s_branch .Lgb_poll9
